# stage-A (compressed-branch) K/V prefetch registers zeroed only on the no-prefetch path, on top of v100
# baseline (speedup 1.0000x reference)
.LBB0_548:
	s_add_i32 s0, s20, -4
	v_mov_b32_e32 v0, s0
	ds_read_b32 v1, v0
	s_cmp_lt_i32 s19, s70
	s_cselect_b64 s[0:1], -1, 0
	s_cmp_ge_i32 s19, s70
	s_waitcnt lgkmcnt(0)
	v_readfirstlane_b32 s21, v1
	s_cbranch_scc1 .Lz16a_0
	v_mov_b32_e32 v0, s20
	ds_read_b32 v0, v0
	s_waitcnt lgkmcnt(0)
	v_readfirstlane_b32 s2, v0
	s_ashr_i32 s3, s2, 31
	s_lshl_b64 s[2:3], s[2:3], 15
	s_add_u32 s2, s26, s2
	s_addc_u32 s3, s27, s3
	v_lshl_add_u64 v[0:1], v[18:19], 1, s[2:3]
	v_lshl_add_u64 v[2:3], v[46:47], 1, s[2:3]
	global_load_dwordx4 v[4:7], v[0:1], off
	s_nop 0
	global_load_dwordx4 v[0:3], v[2:3], off
	s_branch .LBB0_550
.Lz16a_0:
	v_mov_b32_e32 v0, 0
	v_mov_b32_e32 v1, 0
	v_mov_b32_e32 v2, 0
	v_mov_b32_e32 v3, 0
	v_mov_b32_e32 v4, 0
	v_mov_b32_e32 v5, 0
	v_mov_b32_e32 v6, 0
	v_mov_b32_e32 v7, 0

.LBB0_567:
	s_add_i32 s0, s14, -4
	v_mov_b32_e32 v0, s0
	ds_read_b32 v0, v0
	s_cmp_lt_i32 s15, s70
	s_waitcnt vmcnt(0)
	s_cselect_b64 s[0:1], -1, 0
	s_cmp_ge_i32 s15, s70
	s_waitcnt lgkmcnt(0)
	v_readfirstlane_b32 s16, v0
	s_cbranch_scc1 .Lz16a_1
	v_mov_b32_e32 v0, s14
	ds_read_b32 v0, v0
	s_waitcnt lgkmcnt(0)
	v_readfirstlane_b32 s2, v0
	s_ashr_i32 s3, s2, 31
	s_lshl_b64 s[12:13], s[2:3], 15
	s_add_u32 s12, s26, s12
	s_addc_u32 s13, s27, s13
	s_lshl_b32 s2, s2, 6
	s_ashr_i32 s3, s2, 31
	s_lshl_b64 s[2:3], s[2:3], 1
	s_add_u32 s2, s28, s2
	v_lshl_add_u64 v[0:1], v[88:89], 1, s[12:13]
	s_addc_u32 s3, s29, s3
	v_lshl_add_u64 v[2:3], v[90:91], 1, s[12:13]
	global_load_dwordx4 v[70:73], v[0:1], off
	global_load_dwordx4 v[74:77], v[2:3], off
	v_lshl_add_u64 v[0:1], v[92:93], 1, s[2:3]
	v_lshl_add_u64 v[2:3], v[94:95], 1, s[2:3]
	global_load_dwordx4 v[78:81], v[0:1], off
	global_load_dwordx4 v[66:69], v[2:3], off
	s_branch .LBB0_569
.Lz16a_1:
	v_mov_b32_e32 v66, 0
	v_mov_b32_e32 v67, 0
	v_mov_b32_e32 v68, 0
	v_mov_b32_e32 v69, 0
	v_mov_b32_e32 v70, 0
	v_mov_b32_e32 v71, 0
	v_mov_b32_e32 v72, 0
	v_mov_b32_e32 v73, 0
	v_mov_b32_e32 v74, 0
	v_mov_b32_e32 v75, 0
	v_mov_b32_e32 v76, 0
	v_mov_b32_e32 v77, 0
	v_mov_b32_e32 v78, 0
	v_mov_b32_e32 v79, 0
	v_mov_b32_e32 v80, 0
	v_mov_b32_e32 v81, 0
